# early buffer_inv: non-leaders after their arrival atomic returns, XCD leader right behind its buffer_wbl2 (not ahead of it)
# baseline (speedup 1.0000x reference)
.LBB0_1163:
	s_or_b64 exec, exec, s[4:5]
	v_cvt_f32_u32_e32 v4, v2
	s_waitcnt vmcnt(0)
	v_readfirstlane_b32 s2, v3
	v_sub_u32_e32 v3, 0, v2
	v_rcp_iflag_f32_e32 v4, v4
	v_add_u32_e32 v5, s2, v1
	v_mul_f32_e32 v4, 0x4f7ffffe, v4
	v_cvt_u32_f32_e32 v4, v4
	v_mul_lo_u32 v1, v3, v4
	v_mul_hi_u32 v1, v4, v1
	v_add_u32_e32 v1, v4, v1
	v_mul_hi_u32 v1, v5, v1
	v_mul_lo_u32 v3, v1, v2
	v_sub_u32_e32 v3, v5, v3
	v_add_u32_e32 v4, 1, v1
	v_cmp_ge_u32_e32 vcc, v3, v2
	s_nop 1
	v_cndmask_b32_e32 v1, v1, v4, vcc
	v_sub_u32_e32 v4, v3, v2
	v_cndmask_b32_e32 v3, v3, v4, vcc
	v_add_u32_e32 v4, 1, v1
	v_cmp_ge_u32_e32 vcc, v3, v2
	v_add_u32_e32 v3, 1, v5
	s_nop 0
	v_cndmask_b32_e32 v1, v1, v4, vcc
	v_mul_lo_u32 v4, v2, v1
	v_add_u32_e32 v2, v4, v2
	v_cmp_ne_u32_e32 vcc, v3, v2
	s_and_saveexec_b64 s[4:5], vcc
	s_xor_b64 s[4:5], exec, s[4:5]
	s_cbranch_execz .LBB0_1177
	buffer_inv sc1
	v_readlane_b32 s6, v255, 19
	v_readlane_b32 s7, v255, 20
	s_waitcnt lgkmcnt(0)
	s_nop 3
	global_load_dword v0, v173, s[6:7] sc1
	s_waitcnt vmcnt(0)
	v_cmp_eq_u32_e32 vcc, v0, v1
	s_and_saveexec_b64 s[6:7], vcc
	s_cbranch_execz .LBB0_1176
	s_mov_b32 s2, 1
	s_mov_b64 s[8:9], 0
	s_branch .LBB0_1167

.LBB0_1177:
	s_andn2_saveexec_b64 s[4:5], s[4:5]
	s_cbranch_execz .LBB0_1198
	s_mov_b64 s[4:5], exec
	buffer_wbl2 sc1
	buffer_inv sc1
	s_waitcnt lgkmcnt(0)
	s_waitcnt vmcnt(0)
	v_mbcnt_lo_u32_b32 v1, s4, 0
	v_mbcnt_hi_u32_b32 v1, s5, v1
	v_cmp_eq_u32_e32 vcc, 0, v1
	s_and_saveexec_b64 s[6:7], vcc
	s_cbranch_execz .LBB0_1180
	s_bcnt1_i32_b64 s2, s[4:5]
	v_readlane_b32 s4, v255, 17
	v_mov_b32_e32 v2, s2
	v_readlane_b32 s5, v255, 18
	s_nop 4
	global_atomic_add v2, v173, v2, s[4:5] sc0
